# last-layer R3: update-only fast body (both rows latent) with batched loads
# speedup vs baseline: 1.0084x; 1.0028x over previous
; __device__ __forceinline__ void row_pass(const RowPass& R, int gw, int ngw, int lane) {
;     ...
;     for (int row0 = gw; row0 < M; row0 += NR * ngw) {
;         f32x4 v[NR][4]; u32x2 yw[NR][4]; bool act[NR]; float* xrow[NR]; int bbs[NR];
; #pragma unroll
;         for (int k = 0; k < NR; ++k) {
;             const int row = row0 + k * ngw;
;             const int rowc = row < M ? row : row0;
;             const int b = rowc / RPB, i = rowc - b * RPB; const bool isctx = i < CTXL;
;             act[k] = (row < M) && !(isctx && R.skip_ctx);
;             bbs[k] = isctx ? 8 : b;
;             xrow[k] = isctx ? R.xc + ((size_t)b * CTXL + i) * DM : R.out + ((size_t)b * SEQ + (i - CTXL)) * DM;
;             const float* src = R.init ? (isctx ? R.ctx_in + ((size_t)b * CTXL + i) * DM : R.x_in + ((size_t)b * SEQ + (i - CTXL)) * DM) : xrow[k];
;             if (act[k]) {
; #pragma unroll
;                 for (int j = 0; j < 4; ++j) v[k][j] = __builtin_nontemporal_load((const f32x4*)(src + lane * 4 + 256 * j));
;                 if (R.update) { const bf16* yr = R.Y + (size_t)rowc * DM;
; #pragma unroll
;                     for (int j = 0; j < 4; ++j) yw[k][j] = __builtin_nontemporal_load((const u32x2*)(yr + lane * 4 + 256 * j)); }
;             }
;         }
; #pragma unroll
;         for (int k = 0; k < NR; ++k) {
;             if (!act[k]) continue;
;             const int row = row0 + k * ngw, bb = bbs[k];
;             if (R.update) {
;                 f32x4 y[4]; float ss = 0.f;
; #pragma unroll
;                 for (int j = 0; j < 4; ++j) { const u32x2 w = yw[k][j]; y[j] = (f32x4){bflo(w.x), bfhi(w.x), bflo(w.y), bfhi(w.y)};
;                     ss += (y[j][0] * y[j][0] + y[j][1] * y[j][1]) + (y[j][2] * y[j][2] + y[j][3] * y[j][3]); }
;                 const float rstd = __builtin_amdgcn_rsqf(wave_sum(ss) * (1.0f / DM) + EPS);
;                 const float* gate = R.mod + ((size_t)(R.lg * 9 + bb) * NMOD + R.gi) * DM;
; #pragma unroll
;                 for (int j = 0; j < 4; ++j) { const f32x4 g = *(const f32x4*)(gate + lane * 4 + 256 * j), gp = *(const f32x4*)(R.gpost + lane * 4 + 256 * j);
;                     v[k][j] = v[k][j] + g * (y[j] * rstd * gp); }
; __global__ void __launch_bounds__(NTHR, 2) fwd_kernel(Args A_) {
;     ...
;             } else {
;                 const int last = (l == DEPTH - 1);
.Lr3_slow_u:
	s_and_b64 s[46:47], s[50:51], s[52:53]
	s_cmp_lg_u64 s[46:47], 0
	s_cbranch_scc0 .Lr3_slow
	v_lshlrev_b32_e32 v160, 2, v36
	s_add_i32 s72, s7, 0xffffff00
	s_cmp_lg_u64 s[50:51], 0
	s_cselect_b32 s27, s22, s49
	s_cselect_b32 s32, s23, s55
	s_cselect_b32 s37, 24, 20
	s_cselect_b32 s72, s72, s7
	s_cselect_b32 s85, s6, 8
	s_mov_b32 s40, s6
	s_mov_b32 s41, 0
	s_lshl_b64 s[40:41], s[40:41], s37
	s_add_u32 s40, s27, s40
	s_addc_u32 s41, s32, s41
	s_lshl_b32 s72, s72, 12
	s_add_u32 s40, s40, s72
	s_addc_u32 s41, s41, 0
	s_add_i32 s27, s85, s3
	s_mul_hi_i32 s32, s27, 0x6000
	s_mulk_i32 s27, 0x6000
	s_add_u32 s66, s34, s27
	s_addc_u32 s67, s35, s32
	s_add_u32 s66, s66, 0x5000
	s_addc_u32 s67, s67, 0
	s_add_i32 s27, s85, s13
	s_mul_hi_i32 s32, s27, 0x6000
	s_mulk_i32 s27, 0x6000
	s_add_u32 s38, s34, s27
	s_addc_u32 s39, s35, s32
	s_add_u32 s46, s38, 0x1000
	s_addc_u32 s47, s39, 0
	global_load_dwordx4 v[12:15], v160, s[40:41] nt
	global_load_dwordx4 v[8:11], v160, s[40:41] offset:1024 nt
	global_load_dwordx4 v[4:7], v160, s[40:41] offset:2048 nt
	global_load_dwordx4 v[0:3], v160, s[40:41] offset:3072 nt
	global_load_dwordx2 v[54:55], v[46:47], off offset:-1536 nt
	global_load_dwordx2 v[52:53], v[46:47], off offset:-1024 nt
	global_load_dwordx2 v[50:51], v[46:47], off offset:-512 nt
	global_load_dwordx2 v[48:49], v[46:47], off nt
	global_load_dwordx4 v[64:67], v160, s[66:67]
	global_load_dwordx4 v[68:71], v160, s[66:67] offset:1024
	global_load_dwordx4 v[72:75], v160, s[66:67] offset:2048
	global_load_dwordx4 v[76:79], v160, s[66:67] offset:3072
	s_mov_b32 s6, s8
	s_ashr_i32 s7, s8, 31
	s_lshl_b64 s[6:7], s[6:7], 11
	v_lshl_add_u64 v[250:251], v[38:39], 0, s[6:7]
	s_mov_b64 s[6:7], s[52:53]
	s_add_i32 s72, s25, 0xffffff00
	s_cmp_lg_u64 s[6:7], 0
	s_cselect_b32 s27, s22, s49
	s_cselect_b32 s32, s23, s55
	s_cselect_b32 s37, 24, 20
	s_cselect_b32 s72, s72, s25
	s_cselect_b32 s85, s9, 8
	s_mov_b32 s64, s9
	s_mov_b32 s65, 0
	s_lshl_b64 s[64:65], s[64:65], s37
	s_add_u32 s64, s27, s64
	s_addc_u32 s65, s32, s65
	s_lshl_b32 s72, s72, 12
	s_add_u32 s64, s64, s72
	s_addc_u32 s65, s65, 0
	s_add_i32 s27, s85, s3
	s_mul_hi_i32 s32, s27, 0x6000
	s_mulk_i32 s27, 0x6000
	s_add_u32 s10, s34, s27
	s_addc_u32 s11, s35, s32
	s_add_u32 s10, s10, 0x5000
	s_addc_u32 s11, s11, 0
	s_add_i32 s27, s85, s13
	s_mul_hi_i32 s32, s27, 0x6000
	s_mulk_i32 s27, 0x6000
	s_add_u32 s50, s34, s27
	s_addc_u32 s51, s35, s32
	s_add_u32 s52, s50, 0x1000
	s_addc_u32 s53, s51, 0
	global_load_dwordx4 v[16:19], v160, s[64:65] nt
	global_load_dwordx4 v[20:23], v160, s[64:65] offset:1024 nt
	global_load_dwordx4 v[24:27], v160, s[64:65] offset:2048 nt
	global_load_dwordx4 v[28:31], v160, s[64:65] offset:3072 nt
	global_load_dwordx2 v[62:63], v[250:251], off nt
	global_load_dwordx2 v[60:61], v[250:251], off offset:512 nt
	global_load_dwordx2 v[58:59], v[250:251], off offset:1024 nt
	global_load_dwordx2 v[56:57], v[250:251], off offset:1536 nt
	global_load_dwordx4 v[188:191], v160, s[10:11]
	global_load_dwordx4 v[192:195], v160, s[10:11] offset:1024
	global_load_dwordx4 v[196:199], v160, s[10:11] offset:2048
	global_load_dwordx4 v[96:99], v160, s[10:11] offset:3072
	s_waitcnt vmcnt(16)
	v_lshlrev_b32_e32 v32, 16, v54
	v_and_b32_e32 v33, 0xffff0000, v54
	v_lshlrev_b32_e32 v34, 16, v55
	v_and_b32_e32 v35, 0xffff0000, v55
	v_pk_mul_f32 v[166:167], v[32:33], v[32:33]
	v_pk_mul_f32 v[168:169], v[34:35], v[34:35]
	v_lshlrev_b32_e32 v32, 16, v52
	v_and_b32_e32 v33, 0xffff0000, v52
	v_lshlrev_b32_e32 v34, 16, v53
	v_and_b32_e32 v35, 0xffff0000, v53
	v_pk_fma_f32 v[166:167], v[32:33], v[32:33], v[166:167]
	v_pk_fma_f32 v[168:169], v[34:35], v[34:35], v[168:169]
	v_lshlrev_b32_e32 v32, 16, v50
	v_and_b32_e32 v33, 0xffff0000, v50
	v_lshlrev_b32_e32 v34, 16, v51
	v_and_b32_e32 v35, 0xffff0000, v51
	v_pk_fma_f32 v[166:167], v[32:33], v[32:33], v[166:167]
	v_pk_fma_f32 v[168:169], v[34:35], v[34:35], v[168:169]
	v_lshlrev_b32_e32 v32, 16, v48
	v_and_b32_e32 v33, 0xffff0000, v48
	v_lshlrev_b32_e32 v34, 16, v49
	v_and_b32_e32 v35, 0xffff0000, v49
	v_pk_fma_f32 v[166:167], v[32:33], v[32:33], v[166:167]
	v_pk_fma_f32 v[168:169], v[34:35], v[34:35], v[168:169]
	v_pk_add_f32 v[166:167], v[166:167], v[168:169]
	s_nop 0
	v_add_f32_e32 v164, v166, v167
	v_mov_b32_e32 v165, v164
	s_nop 1
	v_permlane32_swap_b32_e32 v165, v164
	v_add_f32_e32 v164, v164, v165
	v_mov_b32_e32 v165, v164
	s_nop 1
	v_permlane16_swap_b32_e32 v165, v164
	v_add_f32_e32 v164, v164, v165
	s_nop 1
	v_add_f32_dpp v164, v164, v164 row_ror:8 row_mask:0xf bank_mask:0xf
	s_nop 1
	v_add_f32_dpp v164, v164, v164 row_ror:4 row_mask:0xf bank_mask:0xf
	s_nop 1
	v_add_f32_dpp v164, v164, v164 row_ror:2 row_mask:0xf bank_mask:0xf
	s_nop 1
	v_add_f32_dpp v164, v164, v164 row_ror:1 row_mask:0xf bank_mask:0xf
	s_nop 0
	v_fmamk_f32 v164, v164, 0x3a800000, v200
	v_rsq_f32_e32 v164, v164
	v_lshlrev_b32_e32 v32, 16, v54
	v_and_b32_e32 v33, 0xffff0000, v54
	v_lshlrev_b32_e32 v34, 16, v55
	v_and_b32_e32 v35, 0xffff0000, v55
	v_pk_mul_f32 v[32:33], v[32:33], v[164:165] op_sel_hi:[1,0]
	v_pk_mul_f32 v[34:35], v[34:35], v[164:165] op_sel_hi:[1,0]
	v_pk_mul_f32 v[32:33], v[218:219], v[32:33]
	v_pk_mul_f32 v[34:35], v[220:221], v[34:35]
	s_waitcnt vmcnt(15)
; __device__ __forceinline__ float bflo(unsigned w) { return __uint_as_float(w << 16); }
; __device__ __forceinline__ float bfhi(unsigned w) { return __uint_as_float(w & 0xffff0000u); }
;     __device__ __forceinline__ void init(int N, int G, int c, int latent_only) { lat = latent_only; b.init(latent_only ? NB * SEQ : M, N, G, c); }
;     __device__ __forceinline__ void init(int c_, unsigned* cnt_) { lat.init(NB * SEQ, FF2, 1, 0); c = c_; cnt = cnt_; }
; __device__ __forceinline__ void row_pass(const RowPass& R, int gw, int ngw, int lane) {
;     ...
; #pragma unroll
;         for (int k = 0; k < NR; ++k) {
;             if (!act[k]) continue;
;             const int row = row0 + k * ngw, bb = bbs[k];
;             if (R.update) {
;                 f32x4 y[4]; float ss = 0.f;
; #pragma unroll
;                 for (int j = 0; j < 4; ++j) { const u32x2 w = yw[k][j]; y[j] = (f32x4){bflo(w.x), bfhi(w.x), bflo(w.y), bfhi(w.y)};
;                     ss += (y[j][0] * y[j][0] + y[j][1] * y[j][1]) + (y[j][2] * y[j][2] + y[j][3] * y[j][3]); }
;                 const float rstd = __builtin_amdgcn_rsqf(wave_sum(ss) * (1.0f / DM) + EPS);
;                 const float* gate = R.mod + ((size_t)(R.lg * 9 + bb) * NMOD + R.gi) * DM;
; #pragma unroll
;                 for (int j = 0; j < 4; ++j) { const f32x4 g = *(const f32x4*)(gate + lane * 4 + 256 * j), gp = *(const f32x4*)(R.gpost + lane * 4 + 256 * j);
;                     v[k][j] = v[k][j] + g * (y[j] * rstd * gp); }
;             }
;             if (R.init || R.update) {
; #pragma unroll
;                 for (int j = 0; j < 4; ++j) __builtin_nontemporal_store(v[k][j], (f32x4*)(xrow[k] + lane * 4 + 256 * j));
	v_pk_fma_f32 v[12:13], v[64:65], v[32:33], v[12:13]
	v_pk_fma_f32 v[14:15], v[66:67], v[34:35], v[14:15]
	global_store_dwordx4 v160, v[12:15], s[40:41] nt
	v_lshlrev_b32_e32 v32, 16, v52
	v_and_b32_e32 v33, 0xffff0000, v52
	v_lshlrev_b32_e32 v34, 16, v53
	v_and_b32_e32 v35, 0xffff0000, v53
	v_pk_mul_f32 v[32:33], v[32:33], v[164:165] op_sel_hi:[1,0]
	v_pk_mul_f32 v[34:35], v[34:35], v[164:165] op_sel_hi:[1,0]
	v_pk_mul_f32 v[32:33], v[222:223], v[32:33]
	v_pk_mul_f32 v[34:35], v[224:225], v[34:35]
	s_waitcnt vmcnt(15)
	v_pk_fma_f32 v[8:9], v[68:69], v[32:33], v[8:9]
	v_pk_fma_f32 v[10:11], v[70:71], v[34:35], v[10:11]
	global_store_dwordx4 v160, v[8:11], s[40:41] offset:1024 nt
	v_lshlrev_b32_e32 v32, 16, v50
	v_and_b32_e32 v33, 0xffff0000, v50
	v_lshlrev_b32_e32 v34, 16, v51
	v_and_b32_e32 v35, 0xffff0000, v51
	v_pk_mul_f32 v[32:33], v[32:33], v[164:165] op_sel_hi:[1,0]
	v_pk_mul_f32 v[34:35], v[34:35], v[164:165] op_sel_hi:[1,0]
	v_pk_mul_f32 v[32:33], v[226:227], v[32:33]
	v_pk_mul_f32 v[34:35], v[228:229], v[34:35]
	s_waitcnt vmcnt(15)
	v_pk_fma_f32 v[4:5], v[72:73], v[32:33], v[4:5]
	v_pk_fma_f32 v[6:7], v[74:75], v[34:35], v[6:7]
	global_store_dwordx4 v160, v[4:7], s[40:41] offset:2048 nt
	v_lshlrev_b32_e32 v32, 16, v48
	v_and_b32_e32 v33, 0xffff0000, v48
	v_lshlrev_b32_e32 v34, 16, v49
	v_and_b32_e32 v35, 0xffff0000, v49
	v_pk_mul_f32 v[32:33], v[32:33], v[164:165] op_sel_hi:[1,0]
	v_pk_mul_f32 v[34:35], v[34:35], v[164:165] op_sel_hi:[1,0]
	v_pk_mul_f32 v[32:33], v[230:231], v[32:33]
	v_pk_mul_f32 v[34:35], v[232:233], v[34:35]
	s_waitcnt vmcnt(15)
	v_pk_fma_f32 v[0:1], v[76:77], v[32:33], v[0:1]
	v_pk_fma_f32 v[2:3], v[78:79], v[34:35], v[2:3]
	global_store_dwordx4 v160, v[0:3], s[40:41] offset:3072 nt
	s_waitcnt vmcnt(8)
	v_lshlrev_b32_e32 v32, 16, v62
	v_and_b32_e32 v33, 0xffff0000, v62
	v_lshlrev_b32_e32 v34, 16, v63
	v_and_b32_e32 v35, 0xffff0000, v63
	v_pk_mul_f32 v[166:167], v[32:33], v[32:33]
	v_pk_mul_f32 v[168:169], v[34:35], v[34:35]
	v_lshlrev_b32_e32 v32, 16, v60
	v_and_b32_e32 v33, 0xffff0000, v60
	v_lshlrev_b32_e32 v34, 16, v61
	v_and_b32_e32 v35, 0xffff0000, v61
	v_pk_fma_f32 v[166:167], v[32:33], v[32:33], v[166:167]
	v_pk_fma_f32 v[168:169], v[34:35], v[34:35], v[168:169]
	v_lshlrev_b32_e32 v32, 16, v58
	v_and_b32_e32 v33, 0xffff0000, v58
	v_lshlrev_b32_e32 v34, 16, v59
	v_and_b32_e32 v35, 0xffff0000, v59
	v_pk_fma_f32 v[166:167], v[32:33], v[32:33], v[166:167]
	v_pk_fma_f32 v[168:169], v[34:35], v[34:35], v[168:169]
	v_lshlrev_b32_e32 v32, 16, v56
	v_and_b32_e32 v33, 0xffff0000, v56
	v_lshlrev_b32_e32 v34, 16, v57
	v_and_b32_e32 v35, 0xffff0000, v57
	v_pk_fma_f32 v[166:167], v[32:33], v[32:33], v[166:167]
	v_pk_fma_f32 v[168:169], v[34:35], v[34:35], v[168:169]
	v_pk_add_f32 v[166:167], v[166:167], v[168:169]
	s_nop 0
	v_add_f32_e32 v164, v166, v167
	v_mov_b32_e32 v165, v164
	s_nop 1
	v_permlane32_swap_b32_e32 v165, v164
	v_add_f32_e32 v164, v164, v165
	v_mov_b32_e32 v165, v164
	s_nop 1
	v_permlane16_swap_b32_e32 v165, v164
	v_add_f32_e32 v164, v164, v165
	s_nop 1
	v_add_f32_dpp v164, v164, v164 row_ror:8 row_mask:0xf bank_mask:0xf
	s_nop 1
	v_add_f32_dpp v164, v164, v164 row_ror:4 row_mask:0xf bank_mask:0xf
	s_nop 1
	v_add_f32_dpp v164, v164, v164 row_ror:2 row_mask:0xf bank_mask:0xf
	s_nop 1
	v_add_f32_dpp v164, v164, v164 row_ror:1 row_mask:0xf bank_mask:0xf
	s_nop 0
	v_fmamk_f32 v164, v164, 0x3a800000, v200
	v_rsq_f32_e32 v164, v164
	v_lshlrev_b32_e32 v32, 16, v62
	v_and_b32_e32 v33, 0xffff0000, v62
	v_lshlrev_b32_e32 v34, 16, v63
	v_and_b32_e32 v35, 0xffff0000, v63
	v_pk_mul_f32 v[32:33], v[32:33], v[164:165] op_sel_hi:[1,0]
	v_pk_mul_f32 v[34:35], v[34:35], v[164:165] op_sel_hi:[1,0]
	v_pk_mul_f32 v[32:33], v[218:219], v[32:33]
	v_pk_mul_f32 v[34:35], v[220:221], v[34:35]
	s_waitcnt vmcnt(7)
	v_pk_fma_f32 v[16:17], v[188:189], v[32:33], v[16:17]
	v_pk_fma_f32 v[18:19], v[190:191], v[34:35], v[18:19]
	global_store_dwordx4 v160, v[16:19], s[64:65] nt
	v_lshlrev_b32_e32 v32, 16, v60
	v_and_b32_e32 v33, 0xffff0000, v60
	v_lshlrev_b32_e32 v34, 16, v61
	v_and_b32_e32 v35, 0xffff0000, v61
	v_pk_mul_f32 v[32:33], v[32:33], v[164:165] op_sel_hi:[1,0]
	v_pk_mul_f32 v[34:35], v[34:35], v[164:165] op_sel_hi:[1,0]
	v_pk_mul_f32 v[32:33], v[222:223], v[32:33]
	v_pk_mul_f32 v[34:35], v[224:225], v[34:35]
	s_waitcnt vmcnt(7)
	v_pk_fma_f32 v[20:21], v[192:193], v[32:33], v[20:21]
	v_pk_fma_f32 v[22:23], v[194:195], v[34:35], v[22:23]
	global_store_dwordx4 v160, v[20:23], s[64:65] offset:1024 nt
	v_lshlrev_b32_e32 v32, 16, v58
	v_and_b32_e32 v33, 0xffff0000, v58
	v_lshlrev_b32_e32 v34, 16, v59
	v_and_b32_e32 v35, 0xffff0000, v59
	v_pk_mul_f32 v[32:33], v[32:33], v[164:165] op_sel_hi:[1,0]
	v_pk_mul_f32 v[34:35], v[34:35], v[164:165] op_sel_hi:[1,0]
	v_pk_mul_f32 v[32:33], v[226:227], v[32:33]
	v_pk_mul_f32 v[34:35], v[228:229], v[34:35]
	s_waitcnt vmcnt(7)
	v_pk_fma_f32 v[24:25], v[196:197], v[32:33], v[24:25]
	v_pk_fma_f32 v[26:27], v[198:199], v[34:35], v[26:27]
	global_store_dwordx4 v160, v[24:27], s[64:65] offset:2048 nt
	v_lshlrev_b32_e32 v32, 16, v56
	v_and_b32_e32 v33, 0xffff0000, v56
	v_lshlrev_b32_e32 v34, 16, v57
	v_and_b32_e32 v35, 0xffff0000, v57
	v_pk_mul_f32 v[32:33], v[32:33], v[164:165] op_sel_hi:[1,0]
	v_pk_mul_f32 v[34:35], v[34:35], v[164:165] op_sel_hi:[1,0]
	v_pk_mul_f32 v[32:33], v[230:231], v[32:33]
	v_pk_mul_f32 v[34:35], v[232:233], v[34:35]
	s_waitcnt vmcnt(7)
	v_pk_fma_f32 v[28:29], v[96:97], v[32:33], v[28:29]
	v_pk_fma_f32 v[30:31], v[98:99], v[34:35], v[30:31]
	global_store_dwordx4 v160, v[28:31], s[64:65] offset:3072 nt
	s_branch .LBB0_148
